# stack23: stack21 + layer-1 input-projection weight conversion split between layer-0 merge-phase tail (non-gate columns) and FFN-up tail (gate columns)
# baseline (speedup 1.0000x reference)
.Lwt_done:
	v_readlane_b32 s37, v250, 58
	s_cmp_lg_u32 s37, 0
	s_cbranch_scc1 .Lwe_done
	s_cmp_gt_u32 s90, 32
	s_cselect_b32 s36, 32, 0
	s_cmp_lt_u32 s21, s36
	s_cbranch_scc1 .Lwe_done
	v_readlane_b32 s40, v250, 52
	v_readlane_b32 s41, v250, 53
	v_readfirstlane_b32 s64, v224
	v_and_b32_e32 v0, 63, v224
	s_lshr_b32 s64, s64, 6
	s_sub_u32 s65, s21, s36
	s_lshl_b32 s65, s65, 3
	s_add_u32 s64, s64, s65
	s_sub_u32 s65, s90, s36
	s_lshl_b32 s65, s65, 3
	s_load_dwordx4 s[44:47], s[40:41], 0x40
	v_lshlrev_b32_e32 v1, 2, v0
	v_add_u32_e32 v2, 0x8840, v1
	v_add_u32_e32 v3, 0x11080, v1
	v_add_u32_e32 v4, 0x198c0, v1
	v_add_u32_e32 v5, 0x22100, v1
	v_add_u32_e32 v6, 0x2a940, v1
	v_add_u32_e32 v7, 0x33180, v1
	v_add_u32_e32 v8, 0x3b9c0, v1
	v_lshlrev_b32_e32 v9, 11, v0
	v_lshrrev_b32_e32 v10, 5, v0
	v_lshl_add_u32 v10, v10, 5, v0
	v_lshlrev_b32_e32 v10, 2, v10
	v_add_u32_e32 v11, 0x8840, v10
	v_add_u32_e32 v12, 0x11080, v10
	v_add_u32_e32 v13, 0x198c0, v10
	v_add_u32_e32 v14, 0x22100, v10
	v_add_u32_e32 v15, 0x2a940, v10
	v_add_u32_e32 v16, 0x33180, v10
	v_add_u32_e32 v17, 0x3b9c0, v10
	s_add_u32 s42, s96, 0x1c829800
	s_addc_u32 s43, s97, 0
	s_waitcnt lgkmcnt(0)
	s_add_u32 s46, s46, 0x2210000
	s_addc_u32 s47, s47, 0
	s_add_u32 s44, s44, 0x1000
	s_addc_u32 s45, s45, 0
	s_mov_b32 s48, s64
.Lwe_loop:
	s_cmp_ge_u32 s48, 0x2600
	s_cbranch_scc1 .Lwe_done
	s_mul_hi_u32 s49, s48, 0x35e50d8
	s_mul_i32 s56, s49, 0x4c
	s_sub_u32 s56, s48, s56
	s_lshr_b32 s57, s56, 2
	s_and_b32 s62, s56, 3
	s_lshl_b32 s62, s62, 6
	s_lshl_b32 s58, s56, 6
	s_mov_b32 s37, 0
	s_cmp_lt_u32 s57, 10
	s_cbranch_scc1 .Lwe_map_done
	s_cmp_lt_u32 s57, 12
	s_cbranch_scc1 .Lwe_map_p16
	s_cmp_lt_u32 s57, 16
	s_cbranch_scc1 .Lwe_map_perm
	s_cmp_lt_u32 s57, 18
	s_cbranch_scc1 .Lwe_map_p16
	s_cmp_eq_u32 s57, 18
	s_cbranch_scc1 .Lwe_map_code
	s_sub_u32 s58, s58, 0xf0
	s_branch .Lwe_map_done

.Lwe_ld_done:
	s_lshl_b32 s66, s49, 5
	s_add_u32 s66, s44, s66
	s_addc_u32 s67, s45, 0
	global_load_dwordx4 v[24:27], v177, s[66:67]
	global_load_dwordx4 v[28:31], v177, s[66:67] offset:16
	s_lshl_b32 s66, s56, 17
	s_lshl_b32 s67, s49, 4
	s_add_u32 s66, s66, s67
	s_add_u32 s66, s42, s66
	s_addc_u32 s67, s43, 0
	s_waitcnt vmcnt(0)
	v_mul_f32_e32 v32, v32, v24
	v_mul_f32_e32 v33, v33, v25
	v_mul_f32_e32 v34, v34, v26
	v_mul_f32_e32 v35, v35, v27
	v_mul_f32_e32 v36, v36, v28
	v_mul_f32_e32 v37, v37, v29
	v_mul_f32_e32 v38, v38, v30
	v_mul_f32_e32 v39, v39, v31
	v_cvt_pk_bf16_f32 v32, v32, v33
	v_cvt_pk_bf16_f32 v33, v34, v35
	v_cvt_pk_bf16_f32 v34, v36, v37
	v_cvt_pk_bf16_f32 v35, v38, v39
	s_cmp_lg_u32 s37, 2
	s_cbranch_scc1 .Lwe_st
	s_sub_u32 s62, 16, s62
	s_max_i32 s62, s62, 0
	v_cmp_gt_u32_e32 vcc, s62, v0
	v_cndmask_b32_e32 v32, 0, v32, vcc
	v_cndmask_b32_e32 v33, 0, v33, vcc
	v_cndmask_b32_e32 v34, 0, v34, vcc
	v_cndmask_b32_e32 v35, 0, v35, vcc
.Lwe_st:
	global_store_dwordx4 v9, v[32:35], s[66:67]
	s_add_u32 s48, s48, s65
	s_branch .Lwe_loop

.Lwi_loop:
	s_cmp_ge_u32 s48, 0x2000
	s_cbranch_scc1 .Lwi_done
	s_mul_hi_u32 s49, s48, 0x4000000
	s_mul_i32 s56, s49, 0x40
	s_sub_u32 s56, s48, s56
	s_add_u32 s56, s56, 0x4c
	s_lshr_b32 s57, s56, 2
	s_and_b32 s62, s56, 3
	s_lshl_b32 s62, s62, 6
	s_lshl_b32 s58, s56, 6
	s_mov_b32 s37, 0
	s_cmp_lt_u32 s57, 10
	s_cbranch_scc1 .Lwi_map_done
	s_cmp_lt_u32 s57, 12
	s_cbranch_scc1 .Lwi_map_p16
	s_cmp_lt_u32 s57, 16
	s_cbranch_scc1 .Lwi_map_perm
	s_cmp_lt_u32 s57, 18
	s_cbranch_scc1 .Lwi_map_p16
	s_cmp_eq_u32 s57, 18
	s_cbranch_scc1 .Lwi_map_code
	s_sub_u32 s58, s58, 0xf0
	s_branch .Lwi_map_done
